# grid barrier: acquire-side L1 invalidate moved to the arrival (issued by idle wave 1 right after the entry s_barrier, overlapping the arrival protocol) instead of after the release on every workgroup'
# speedup vs baseline: 1.0135x; 1.0104x over previous
; DI unsigned xb_ld(unsigned* p)              { return __hip_atomic_load(p, __ATOMIC_RELAXED, __HIP_MEMORY_SCOPE_AGENT); }
; DI unsigned xb_add(unsigned* p, unsigned v) { return __hip_atomic_fetch_add(p, v, __ATOMIC_RELAXED, __HIP_MEMORY_SCOPE_AGENT); }
; DI void xcd_barrier_complete(unsigned* bar, unsigned x, unsigned& nloc, unsigned& nx) {
;     const unsigned G = gridDim.x * gridDim.y * gridDim.z;
;     unsigned sum, cnt, mine, sp = 0u;
;     for (;;) {
;         sum = 0u; cnt = 0u; mine = 0u;
; #pragma unroll
;         for (unsigned j = 0; j < 16; ++j) { const unsigned c = xb_ld(&bar[XB_XCNT(j)]); sum += c; cnt += (c > 0u) ? 1u : 0u; mine = (j == x) ? c : mine; }
; DI void xcd_barrier(const XcdBarrier& b) {
;     asm volatile("s_waitcnt vmcnt(0)" ::: "memory");
;     __syncthreads();
;     if (threadIdx.x == 0) {
;         unsigned* bar = b.bar;
;         __builtin_amdgcn_s_waitcnt(0);
;         unsigned nloc = b.st[0], nx = b.st[1];
;         if (nloc == 0u) { xcd_barrier_complete(bar, b.x, nloc, nx); b.st[0] = nloc; b.st[1] = nx; }
;         const unsigned old = xb_add(&bar[XB_XSUB(b.x)], 1u);
.LBB0_99:
	s_or_b64 exec, exec, s[6:7]
	s_waitcnt vmcnt(0)
	s_barrier
	s_cselect_b32 s98, 1, 0
	v_readfirstlane_b32 s100, v208
	s_lshr_b32 s100, s100, 6
	s_cmp_eq_u32 s100, 1
	s_cbranch_scc0 .Lea_0
	buffer_inv sc1
	s_waitcnt vmcnt(0)
.Lea_0:
	s_cmp_lg_u32 s98, 0
	s_and_saveexec_b64 s[8:9], s[4:5]
	s_xor_b64 s[4:5], exec, s[8:9]
	s_lshl_b32 s6, s81, 6
	s_mov_b32 s7, 0
	s_or_saveexec_b64 s[4:5], s[4:5]
	v_writelane_b32 v254, s92, 23
	v_mov_b64_e32 v[136:137], s[6:7]
	s_nop 0
	v_writelane_b32 v254, s93, 24
	s_xor_b64 exec, exec, s[4:5]
	s_cbranch_execz .LBB0_154
	s_add_i32 s3, 0, 0x22000
	v_mov_b32_e32 v0, s3
	s_waitcnt vmcnt(0) expcnt(0) lgkmcnt(0)
	ds_read_b32 v2, v0
	s_add_i32 s3, 0, 0x22004
	v_mov_b32_e32 v0, s3
	ds_read_b32 v0, v0
	s_waitcnt lgkmcnt(1)
	v_cmp_ne_u32_e32 vcc, 0, v2
	s_cbranch_vccnz .LBB0_117
	s_add_u32 s6, s76, 0x80200
	s_addc_u32 s7, s77, 0
	s_add_u32 s8, s76, 0x80400
	s_addc_u32 s9, s77, 0
	s_add_u32 s10, s76, 0x80500
	s_addc_u32 s11, s77, 0
	s_add_u32 s14, s76, 0x80600
	s_addc_u32 s15, s77, 0
	s_add_u32 s18, s76, 0x80700
	s_addc_u32 s19, s77, 0
	s_add_u32 s22, s76, 0x80800
	s_addc_u32 s23, s77, 0
	s_add_u32 s40, s76, 0x80900
	s_addc_u32 s41, s77, 0
	s_add_u32 s42, s76, 0x80a00
	s_addc_u32 s43, s77, 0
	s_add_u32 s44, s76, 0x80b00
	s_addc_u32 s45, s77, 0
	s_add_u32 s46, s76, 0x80c00
	s_addc_u32 s47, s77, 0
	s_add_u32 s48, s76, 0x80d00
	s_addc_u32 s49, s77, 0
	s_add_u32 s50, s76, 0x80e00
	s_addc_u32 s51, s77, 0
	s_add_u32 s60, s76, 0x80f00
	s_addc_u32 s61, s77, 0
	s_add_u32 s62, s76, 0x81000
	s_addc_u32 s63, s77, 0
	s_add_u32 s78, s76, 0x81100
	s_addc_u32 s79, s77, 0
	s_add_u32 s88, s76, 0x81200
	s_mul_i32 s3, s93, s82
	s_addc_u32 s89, s77, 0
	s_mul_i32 s3, s3, s92
	s_add_u32 s92, s76, 0x81300
	s_addc_u32 s93, s77, 0
	s_mov_b32 s12, 1
	v_mov_b32_e32 v16, 0
	s_branch .LBB0_105

; DI unsigned xb_ld(unsigned* p)              { return __hip_atomic_load(p, __ATOMIC_RELAXED, __HIP_MEMORY_SCOPE_AGENT); }
; #define XB_SPIN(cond, bar) do { unsigned _sp = 0; while (cond) { __builtin_amdgcn_s_sleep(1); \
;     if ((++_sp & 255u) == 0u) { if (xb_ld(&(bar)[XB_TMO])) break; if (_sp > XB_SPIN_CAP) { atomicAdd(&(bar)[XB_TMO], 1u); break; } } } } while (0)
; DI void xcd_barrier(const XcdBarrier& b) {
;     ...
;         } else {
;             XB_SPIN(xb_ld(&bar[XB_XGEN(b.x)]) == gen, bar);
;             __builtin_amdgcn_fence(__ATOMIC_ACQUIRE, "agent");
;             asm volatile("s_waitcnt vmcnt(0)" ::: "memory");
.LBB0_132:
	s_or_b64 exec, exec, s[14:15]
	s_waitcnt vmcnt(0)
	s_waitcnt vmcnt(0)

; DI unsigned xb_ld(unsigned* p)              { return __hip_atomic_load(p, __ATOMIC_RELAXED, __HIP_MEMORY_SCOPE_AGENT); }
; DI unsigned xb_add(unsigned* p, unsigned v) { return __hip_atomic_fetch_add(p, v, __ATOMIC_RELAXED, __HIP_MEMORY_SCOPE_AGENT); }
; #define XB_SPIN(cond, bar) do { unsigned _sp = 0; while (cond) { __builtin_amdgcn_s_sleep(1); \
;     if ((++_sp & 255u) == 0u) { if (xb_ld(&(bar)[XB_TMO])) break; if (_sp > XB_SPIN_CAP) { atomicAdd(&(bar)[XB_TMO], 1u); break; } } } } while (0)
; DI void xcd_barrier(const XcdBarrier& b) {
;     ...
;             if (og + 1u == (tg + 1u) * nx) xb_add(&bar[XB_TOPGEN], 1u);
;             else XB_SPIN(xb_ld(&bar[XB_TOPGEN]) == tg, bar);
;             __builtin_amdgcn_fence(__ATOMIC_ACQUIRE, "agent");
;             xb_add(&bar[XB_XGEN(b.x)], 1u);
;             asm volatile("s_waitcnt vmcnt(0)" ::: "memory");
.LBB0_150:
	s_or_b64 exec, exec, s[14:15]
	s_mov_b64 s[14:15], exec
	v_mbcnt_lo_u32_b32 v0, s14, 0
	v_mbcnt_hi_u32_b32 v0, s15, v0
	v_cmp_eq_u32_e32 vcc, 0, v0
	s_waitcnt vmcnt(0)
	s_and_saveexec_b64 s[18:19], vcc
	s_cbranch_execz .LBB0_152
	s_bcnt1_i32_b64 s3, s[14:15]
	v_mov_b32_e32 v0, 0x2000
	v_mov_b32_e32 v1, s3
	global_atomic_add v0, v1, s[8:9] offset:1024

; DI unsigned xb_ld(unsigned* p)              { return __hip_atomic_load(p, __ATOMIC_RELAXED, __HIP_MEMORY_SCOPE_AGENT); }
; DI unsigned xb_add(unsigned* p, unsigned v) { return __hip_atomic_fetch_add(p, v, __ATOMIC_RELAXED, __HIP_MEMORY_SCOPE_AGENT); }
; DI void xcd_barrier_complete(unsigned* bar, unsigned x, unsigned& nloc, unsigned& nx) {
;     const unsigned G = gridDim.x * gridDim.y * gridDim.z;
;     unsigned sum, cnt, mine, sp = 0u;
;     for (;;) {
;         sum = 0u; cnt = 0u; mine = 0u;
; #pragma unroll
;         for (unsigned j = 0; j < 16; ++j) { const unsigned c = xb_ld(&bar[XB_XCNT(j)]); sum += c; cnt += (c > 0u) ? 1u : 0u; mine = (j == x) ? c : mine; }
; DI void xcd_barrier(const XcdBarrier& b) {
;     asm volatile("s_waitcnt vmcnt(0)" ::: "memory");
;     __syncthreads();
;     if (threadIdx.x == 0) {
;         unsigned* bar = b.bar;
;         __builtin_amdgcn_s_waitcnt(0);
;         unsigned nloc = b.st[0], nx = b.st[1];
;         if (nloc == 0u) { xcd_barrier_complete(bar, b.x, nloc, nx); b.st[0] = nloc; b.st[1] = nx; }
;         const unsigned old = xb_add(&bar[XB_XSUB(b.x)], 1u);
.LBB0_296:
	s_mul_i32 s0, s93, s92
	s_mul_i32 s0, s0, s82
	v_writelane_b32 v253, s0, 1
	s_add_u32 s0, s76, 0x80200
	s_addc_u32 s1, s77, 0
	v_writelane_b32 v253, s0, 2
	v_lshl_add_u64 v[0:1], v[136:137], 2, s[84:85]
	s_waitcnt vmcnt(0)
	s_waitcnt vmcnt(0)
	v_writelane_b32 v253, s1, 3
	s_add_u32 s0, s76, 0x80400
	s_addc_u32 s1, s77, 0
	v_writelane_b32 v254, s0, 20
	s_barrier
	s_cselect_b32 s98, 1, 0
	v_readfirstlane_b32 s100, v208
	s_lshr_b32 s100, s100, 6
	s_cmp_eq_u32 s100, 1
	s_cbranch_scc0 .Lea_1
	buffer_inv sc1
	s_waitcnt vmcnt(0)
.Lea_1:
	s_cmp_lg_u32 s98, 0
	s_nop 0
	v_writelane_b32 v254, s1, 21
	s_add_u32 s0, s76, 0x80500
	s_addc_u32 s1, s77, 0
	v_writelane_b32 v254, s0, 29
	s_nop 1
	v_writelane_b32 v254, s1, 30
	s_add_u32 s0, s76, 0x80600
	s_addc_u32 s1, s77, 0
	v_writelane_b32 v254, s0, 39
	s_nop 1
	v_writelane_b32 v254, s1, 40
	s_add_u32 s0, s76, 0x80700
	s_addc_u32 s1, s77, 0
	v_writelane_b32 v254, s0, 18
	s_nop 1
	v_writelane_b32 v254, s1, 19
	s_add_u32 s0, s76, 0x80800
	s_addc_u32 s1, s77, 0
	v_writelane_b32 v254, s0, 41
	s_nop 1
	v_writelane_b32 v254, s1, 42
	s_add_u32 s0, s76, 0x80900
	s_addc_u32 s1, s77, 0
	v_writelane_b32 v254, s0, 43
	s_nop 1
	v_writelane_b32 v254, s1, 44
	s_add_u32 s0, s76, 0x80a00
	s_addc_u32 s1, s77, 0
	v_writelane_b32 v254, s0, 45
	s_nop 1
	v_writelane_b32 v254, s1, 46
	s_add_u32 s0, s76, 0x80b00
	s_addc_u32 s1, s77, 0
	v_writelane_b32 v254, s0, 47
	s_nop 1
	v_writelane_b32 v254, s1, 48
	s_add_u32 s0, s76, 0x80c00
	s_addc_u32 s1, s77, 0
	v_writelane_b32 v254, s0, 49
	s_nop 1
	v_writelane_b32 v254, s1, 50
	s_add_u32 s0, s76, 0x80d00
	s_addc_u32 s1, s77, 0
	v_writelane_b32 v254, s0, 51
	s_nop 1
	v_writelane_b32 v254, s1, 52
	s_add_u32 s0, s76, 0x80e00
	s_addc_u32 s1, s77, 0
	v_writelane_b32 v254, s0, 53
	s_nop 1
	v_writelane_b32 v254, s1, 54
	s_add_u32 s0, s76, 0x80f00
	s_addc_u32 s1, s77, 0
	v_writelane_b32 v254, s0, 55
	s_nop 1
	v_writelane_b32 v254, s1, 56
	s_add_u32 s0, s76, 0x81000
	s_addc_u32 s1, s77, 0
	v_writelane_b32 v254, s0, 57
	s_nop 1
	v_writelane_b32 v254, s1, 58
	s_add_u32 s0, s76, 0x81100
	s_addc_u32 s1, s77, 0
	v_writelane_b32 v254, s0, 59
	s_nop 1
	v_writelane_b32 v254, s1, 60
	s_add_u32 s0, s76, 0x81200
	s_addc_u32 s1, s77, 0
	v_writelane_b32 v254, s0, 61
	s_nop 1
	v_writelane_b32 v254, s1, 62
	s_add_u32 s0, s76, 0x81300
	s_addc_u32 s1, s77, 0
	v_writelane_b32 v254, s0, 63
	s_cmp_eq_u32 s81, 15
	s_nop 0
	v_writelane_b32 v253, s1, 0
	s_cselect_b64 s[0:1], -1, 0
	v_writelane_b32 v253, s0, 34
	s_cmp_eq_u32 s81, 14
	s_nop 0
	v_writelane_b32 v253, s1, 35
	s_cselect_b64 s[0:1], -1, 0
	v_writelane_b32 v253, s0, 32
	s_cmp_eq_u32 s81, 13
	s_nop 0
	v_writelane_b32 v253, s1, 33
	s_cselect_b64 s[0:1], -1, 0
	v_writelane_b32 v253, s0, 30
	s_cmp_eq_u32 s81, 12
	s_nop 0
	v_writelane_b32 v253, s1, 31
	s_cselect_b64 s[0:1], -1, 0
	v_writelane_b32 v253, s0, 28
	s_cmp_eq_u32 s81, 11
	s_nop 0
	v_writelane_b32 v253, s1, 29
	s_cselect_b64 s[0:1], -1, 0
	v_writelane_b32 v253, s0, 26
	s_cmp_eq_u32 s81, 10
	s_nop 0
	v_writelane_b32 v253, s1, 27
	s_cselect_b64 s[0:1], -1, 0
	v_writelane_b32 v253, s0, 24
	s_cmp_eq_u32 s81, 9
	s_nop 0
	v_writelane_b32 v253, s1, 25
	s_cselect_b64 s[0:1], -1, 0
	v_writelane_b32 v253, s0, 22
	s_cmp_eq_u32 s81, 8
	s_nop 0
	v_writelane_b32 v253, s1, 23
	s_cselect_b64 s[0:1], -1, 0
	v_writelane_b32 v253, s0, 20
	s_cmp_eq_u32 s81, 7
	s_nop 0
	v_writelane_b32 v253, s1, 21
	s_cselect_b64 s[0:1], -1, 0
	v_writelane_b32 v253, s0, 18
	s_cmp_eq_u32 s81, 6
	s_nop 0
	v_writelane_b32 v253, s1, 19
	s_cselect_b64 s[0:1], -1, 0
	v_writelane_b32 v253, s0, 16
	s_cmp_eq_u32 s81, 5
	s_nop 0
	v_writelane_b32 v253, s1, 17
	s_cselect_b64 s[0:1], -1, 0
	v_writelane_b32 v253, s0, 14
	s_cmp_eq_u32 s81, 4
	s_nop 0
	v_writelane_b32 v253, s1, 15
	s_cselect_b64 s[0:1], -1, 0
	v_writelane_b32 v253, s0, 12
	s_cmp_eq_u32 s81, 3
	s_nop 0
	v_writelane_b32 v253, s1, 13
	s_cselect_b64 s[0:1], -1, 0
	v_writelane_b32 v253, s0, 10
	s_cmp_eq_u32 s81, 2
	s_nop 0
	v_writelane_b32 v253, s1, 11
	s_cselect_b64 s[0:1], -1, 0
	v_writelane_b32 v253, s0, 8
	s_cmp_eq_u32 s81, 1
	s_nop 0
	v_writelane_b32 v253, s1, 9
	s_cselect_b64 s[0:1], -1, 0
	v_writelane_b32 v253, s0, 6
	s_cmp_eq_u32 s81, 0
	s_nop 0
	v_writelane_b32 v253, s1, 7
	s_cselect_b64 s[0:1], -1, 0
	v_writelane_b32 v253, s0, 4
	s_nop 1
	v_writelane_b32 v253, s1, 5
	s_mov_b64 s[0:1], 0x1400
	v_lshl_add_u64 v[164:165], v[0:1], 0, s[0:1]
	s_mov_b64 s[0:1], 0x2400
	v_lshl_add_u64 v[162:163], v[0:1], 0, s[0:1]
	s_add_u32 s0, s76, 0x83400
	s_addc_u32 s1, s77, 0
	v_writelane_b32 v253, s0, 36
	s_nop 1
	v_writelane_b32 v253, s1, 37
	s_add_u32 s0, s76, 0x83500
	s_addc_u32 s1, s77, 0
	v_writelane_b32 v253, s0, 38
	s_nop 1
	v_writelane_b32 v253, s1, 39
	s_mov_b64 s[0:1], exec
	v_readlane_b32 s4, v254, 16
	v_readlane_b32 s5, v254, 17
	s_and_b64 s[4:5], s[0:1], s[4:5]
	s_xor_b64 s[20:21], s[4:5], s[0:1]
	s_mov_b64 exec, s[4:5]
	s_cbranch_execz .LBB0_345
	s_add_i32 s0, 0, 0x22000
	v_mov_b32_e32 v0, s0
	s_waitcnt vmcnt(0) expcnt(0) lgkmcnt(0)
	ds_read_b32 v2, v0
	s_add_i32 s0, 0, 0x22004
	v_mov_b32_e32 v0, s0
	ds_read_b32 v0, v0
	s_waitcnt lgkmcnt(1)
	v_cmp_ne_u32_e32 vcc, 0, v2
	s_cbranch_vccnz .LBB0_312
	s_mov_b32 s0, 1
	v_mov_b32_e32 v16, 0
	s_branch .LBB0_300

; DI unsigned xb_ld(unsigned* p)              { return __hip_atomic_load(p, __ATOMIC_RELAXED, __HIP_MEMORY_SCOPE_AGENT); }
; #define XB_SPIN(cond, bar) do { unsigned _sp = 0; while (cond) { __builtin_amdgcn_s_sleep(1); \
;     if ((++_sp & 255u) == 0u) { if (xb_ld(&(bar)[XB_TMO])) break; if (_sp > XB_SPIN_CAP) { atomicAdd(&(bar)[XB_TMO], 1u); break; } } } } while (0)
; DI void xcd_barrier(const XcdBarrier& b) {
;     ...
;         } else {
;             XB_SPIN(xb_ld(&bar[XB_XGEN(b.x)]) == gen, bar);
;             __builtin_amdgcn_fence(__ATOMIC_ACQUIRE, "agent");
;             asm volatile("s_waitcnt vmcnt(0)" ::: "memory");
.LBB0_325:
	s_or_b64 exec, exec, s[38:39]
	s_waitcnt vmcnt(0)
	s_waitcnt vmcnt(0)

; DI unsigned xb_ld(unsigned* p)              { return __hip_atomic_load(p, __ATOMIC_RELAXED, __HIP_MEMORY_SCOPE_AGENT); }
; DI unsigned xb_add(unsigned* p, unsigned v) { return __hip_atomic_fetch_add(p, v, __ATOMIC_RELAXED, __HIP_MEMORY_SCOPE_AGENT); }
; #define XB_SPIN(cond, bar) do { unsigned _sp = 0; while (cond) { __builtin_amdgcn_s_sleep(1); \
;     if ((++_sp & 255u) == 0u) { if (xb_ld(&(bar)[XB_TMO])) break; if (_sp > XB_SPIN_CAP) { atomicAdd(&(bar)[XB_TMO], 1u); break; } } } } while (0)
; DI void xcd_barrier(const XcdBarrier& b) {
;     ...
;             if (og + 1u == (tg + 1u) * nx) xb_add(&bar[XB_TOPGEN], 1u);
;             else XB_SPIN(xb_ld(&bar[XB_TOPGEN]) == tg, bar);
;             __builtin_amdgcn_fence(__ATOMIC_ACQUIRE, "agent");
;             xb_add(&bar[XB_XGEN(b.x)], 1u);
;             asm volatile("s_waitcnt vmcnt(0)" ::: "memory");
.LBB0_343:
	s_or_b64 exec, exec, s[38:39]
	v_mov_b32_e32 v0, 1
	s_waitcnt vmcnt(0)
	global_atomic_add v[162:163], v0, off
	s_waitcnt vmcnt(0)

; DI void xcd_barrier(const XcdBarrier& b) {
;     asm volatile("s_waitcnt vmcnt(0)" ::: "memory");
;     __syncthreads();
;     if (threadIdx.x == 0) {
;         unsigned* bar = b.bar;
;         __builtin_amdgcn_s_waitcnt(0);
;         unsigned nloc = b.st[0], nx = b.st[1];
;         if (nloc == 0u) { xcd_barrier_complete(bar, b.x, nloc, nx); b.st[0] = nloc; b.st[1] = nx; }
.LBB0_360:
	s_waitcnt vmcnt(0)
	s_barrier
	s_cselect_b32 s98, 1, 0
	v_readfirstlane_b32 s100, v208
	s_lshr_b32 s100, s100, 6
	s_cmp_eq_u32 s100, 1
	s_cbranch_scc0 .Lea_2
	buffer_inv sc1
	s_waitcnt vmcnt(0)
.Lea_2:
	s_cmp_lg_u32 s98, 0
	s_mov_b64 s[20:21], exec
	v_readlane_b32 s0, v254, 16
	v_readlane_b32 s1, v254, 17
	s_and_b64 s[0:1], s[20:21], s[0:1]
	s_mov_b64 exec, s[0:1]
	s_cbranch_execz .LBB0_408
	s_add_i32 s0, 0, 0x22000
	v_mov_b32_e32 v0, s0
	s_waitcnt vmcnt(0) expcnt(0) lgkmcnt(0)
	ds_read_b32 v2, v0
	s_add_i32 s0, 0, 0x22004
	v_mov_b32_e32 v0, s0
	ds_read_b32 v0, v0
	s_waitcnt lgkmcnt(1)
	v_cmp_ne_u32_e32 vcc, 0, v2
	s_cbranch_vccnz .LBB0_376
	s_mov_b32 s0, 1
	v_mov_b32_e32 v16, 0
	s_branch .LBB0_364

; DI unsigned xb_ld(unsigned* p)              { return __hip_atomic_load(p, __ATOMIC_RELAXED, __HIP_MEMORY_SCOPE_AGENT); }
; #define XB_SPIN(cond, bar) do { unsigned _sp = 0; while (cond) { __builtin_amdgcn_s_sleep(1); \
;     if ((++_sp & 255u) == 0u) { if (xb_ld(&(bar)[XB_TMO])) break; if (_sp > XB_SPIN_CAP) { atomicAdd(&(bar)[XB_TMO], 1u); break; } } } } while (0)
; DI void xcd_barrier(const XcdBarrier& b) {
;     ...
;         } else {
;             XB_SPIN(xb_ld(&bar[XB_XGEN(b.x)]) == gen, bar);
;             __builtin_amdgcn_fence(__ATOMIC_ACQUIRE, "agent");
;             asm volatile("s_waitcnt vmcnt(0)" ::: "memory");
.LBB0_389:
	s_or_b64 exec, exec, s[24:25]
	s_waitcnt vmcnt(0)
	s_waitcnt vmcnt(0)

; DI unsigned xb_add(unsigned* p, unsigned v) { return __hip_atomic_fetch_add(p, v, __ATOMIC_RELAXED, __HIP_MEMORY_SCOPE_AGENT); }
; DI void xcd_barrier(const XcdBarrier& b) {
;     ...
;             __builtin_amdgcn_fence(__ATOMIC_ACQUIRE, "agent");
;             xb_add(&bar[XB_XGEN(b.x)], 1u);
;             asm volatile("s_waitcnt vmcnt(0)" ::: "memory");
.LBB0_407:
	s_or_b64 exec, exec, s[22:23]
	v_mov_b32_e32 v0, 1
	s_waitcnt vmcnt(0)
	global_atomic_add v[162:163], v0, off
	s_waitcnt vmcnt(0)

; DI void xcd_barrier(const XcdBarrier& b) {
;     asm volatile("s_waitcnt vmcnt(0)" ::: "memory");
;     __syncthreads();
;     if (threadIdx.x == 0) {
;         unsigned* bar = b.bar;
;         __builtin_amdgcn_s_waitcnt(0);
;         unsigned nloc = b.st[0], nx = b.st[1];
;         if (nloc == 0u) { xcd_barrier_complete(bar, b.x, nloc, nx); b.st[0] = nloc; b.st[1] = nx; }
.LBB0_566:
	s_setprio 0
	s_waitcnt vmcnt(0)
	s_barrier
	s_cselect_b32 s98, 1, 0
	v_readfirstlane_b32 s100, v208
	s_lshr_b32 s100, s100, 6
	s_cmp_eq_u32 s100, 1
	s_cbranch_scc0 .Lea_3
	buffer_inv sc1
	s_waitcnt vmcnt(0)
.Lea_3:
	s_cmp_lg_u32 s98, 0
	s_mov_b64 s[0:1], exec
	v_readlane_b32 s4, v254, 16
	v_readlane_b32 s5, v254, 17
	s_and_b64 s[4:5], s[0:1], s[4:5]
	s_xor_b64 s[20:21], s[4:5], s[0:1]
	s_mov_b64 exec, s[4:5]
	s_cbranch_execz .LBB0_615
	s_add_i32 s0, 0, 0x22000
	v_mov_b32_e32 v0, s0
	s_waitcnt vmcnt(0) expcnt(0) lgkmcnt(0)
	ds_read_b32 v2, v0
	s_add_i32 s0, 0, 0x22004
	v_mov_b32_e32 v0, s0
	ds_read_b32 v0, v0
	s_waitcnt lgkmcnt(1)
	v_cmp_ne_u32_e32 vcc, 0, v2
	s_cbranch_vccnz .LBB0_582
	s_mov_b32 s0, 1
	v_mov_b32_e32 v16, 0
	s_branch .LBB0_570

; DI unsigned xb_ld(unsigned* p)              { return __hip_atomic_load(p, __ATOMIC_RELAXED, __HIP_MEMORY_SCOPE_AGENT); }
; #define XB_SPIN(cond, bar) do { unsigned _sp = 0; while (cond) { __builtin_amdgcn_s_sleep(1); \
;     if ((++_sp & 255u) == 0u) { if (xb_ld(&(bar)[XB_TMO])) break; if (_sp > XB_SPIN_CAP) { atomicAdd(&(bar)[XB_TMO], 1u); break; } } } } while (0)
; DI void xcd_barrier(const XcdBarrier& b) {
;     ...
;             XB_SPIN(xb_ld(&bar[XB_XGEN(b.x)]) == gen, bar);
;             __builtin_amdgcn_fence(__ATOMIC_ACQUIRE, "agent");
;             asm volatile("s_waitcnt vmcnt(0)" ::: "memory");
.LBB0_595:
	s_or_b64 exec, exec, s[26:27]
	s_waitcnt vmcnt(0)
	s_waitcnt vmcnt(0)

; DI unsigned xb_add(unsigned* p, unsigned v) { return __hip_atomic_fetch_add(p, v, __ATOMIC_RELAXED, __HIP_MEMORY_SCOPE_AGENT); }
; DI void xcd_barrier(const XcdBarrier& b) {
;     ...
;             __builtin_amdgcn_fence(__ATOMIC_ACQUIRE, "agent");
;             xb_add(&bar[XB_XGEN(b.x)], 1u);
;             asm volatile("s_waitcnt vmcnt(0)" ::: "memory");
.LBB0_613:
	s_or_b64 exec, exec, s[26:27]
	v_mov_b32_e32 v0, 1
	s_waitcnt vmcnt(0)
	global_atomic_add v[162:163], v0, off
	s_waitcnt vmcnt(0)

; DI void xcd_barrier(const XcdBarrier& b) {
;     ...
;     if (threadIdx.x == 0) {
;         unsigned* bar = b.bar;
;         __builtin_amdgcn_s_waitcnt(0);
;         unsigned nloc = b.st[0], nx = b.st[1];
;         if (nloc == 0u) { xcd_barrier_complete(bar, b.x, nloc, nx); b.st[0] = nloc; b.st[1] = nx; }
.Lea_4:
	s_cmp_lg_u32 s98, 0
	s_mov_b64 s[20:21], exec
	v_readlane_b32 s0, v254, 16
	v_readlane_b32 s1, v254, 17
	v_readlane_b32 s92, v253, 2
	s_and_b64 s[0:1], s[20:21], s[0:1]
	v_readlane_b32 s12, v253, 1
	v_readlane_b32 s93, v253, 3
	s_mov_b64 exec, s[0:1]
	s_cbranch_execz .LBB0_672
	s_add_i32 s0, 0, 0x22000
	v_mov_b32_e32 v0, s0
	s_waitcnt vmcnt(0) expcnt(0) lgkmcnt(0)
	ds_read_b32 v2, v0
	s_add_i32 s0, 0, 0x22004
	v_mov_b32_e32 v0, s0
	ds_read_b32 v0, v0
	s_waitcnt lgkmcnt(1)
	v_cmp_ne_u32_e32 vcc, 0, v2
	s_cbranch_vccnz .LBB0_640
	s_mov_b32 s0, 1
	v_mov_b32_e32 v16, 0
	s_branch .LBB0_628

; DI void xcd_barrier(const XcdBarrier& b) {
;     asm volatile("s_waitcnt vmcnt(0)" ::: "memory");
;     __syncthreads();
;     if (threadIdx.x == 0) {
;         unsigned* bar = b.bar;
;         __builtin_amdgcn_s_waitcnt(0);
;         unsigned nloc = b.st[0], nx = b.st[1];
;         if (nloc == 0u) { xcd_barrier_complete(bar, b.x, nloc, nx); b.st[0] = nloc; b.st[1] = nx; }
.LBB0_716:
	s_waitcnt vmcnt(0)
	s_waitcnt lgkmcnt(0)
	s_barrier
	s_cselect_b32 s98, 1, 0
	v_readfirstlane_b32 s100, v208
	s_lshr_b32 s100, s100, 6
	s_cmp_eq_u32 s100, 1
	s_cbranch_scc0 .Lea_5
	buffer_inv sc1
	s_waitcnt vmcnt(0)
.Lea_5:
	s_cmp_lg_u32 s98, 0
	s_mov_b64 s[16:17], exec
	v_readlane_b32 s0, v254, 16
	v_readlane_b32 s1, v254, 17
	s_and_b64 s[0:1], s[16:17], s[0:1]
	s_mov_b64 exec, s[0:1]
	s_cbranch_execz .LBB0_764
	s_add_i32 s0, 0, 0x22000
	v_mov_b32_e32 v0, s0
	s_waitcnt vmcnt(0) expcnt(0) lgkmcnt(0)
	ds_read_b32 v2, v0
	s_add_i32 s0, 0, 0x22004
	v_mov_b32_e32 v0, s0
	ds_read_b32 v0, v0
	s_waitcnt lgkmcnt(1)
	v_cmp_ne_u32_e32 vcc, 0, v2
	s_cbranch_vccnz .LBB0_732
	s_mov_b32 s0, 1
	v_mov_b32_e32 v16, 0
	s_branch .LBB0_720

; DI unsigned xb_ld(unsigned* p)              { return __hip_atomic_load(p, __ATOMIC_RELAXED, __HIP_MEMORY_SCOPE_AGENT); }
; #define XB_SPIN(cond, bar) do { unsigned _sp = 0; while (cond) { __builtin_amdgcn_s_sleep(1); \
;     if ((++_sp & 255u) == 0u) { if (xb_ld(&(bar)[XB_TMO])) break; if (_sp > XB_SPIN_CAP) { atomicAdd(&(bar)[XB_TMO], 1u); break; } } } } while (0)
; DI void xcd_barrier(const XcdBarrier& b) {
;     ...
;             XB_SPIN(xb_ld(&bar[XB_XGEN(b.x)]) == gen, bar);
;             __builtin_amdgcn_fence(__ATOMIC_ACQUIRE, "agent");
;             asm volatile("s_waitcnt vmcnt(0)" ::: "memory");
.LBB0_745:
	s_or_b64 exec, exec, s[22:23]
	s_waitcnt vmcnt(0)
	s_waitcnt vmcnt(0)

; DI unsigned xb_add(unsigned* p, unsigned v) { return __hip_atomic_fetch_add(p, v, __ATOMIC_RELAXED, __HIP_MEMORY_SCOPE_AGENT); }
; DI void xcd_barrier(const XcdBarrier& b) {
;     ...
;             __builtin_amdgcn_fence(__ATOMIC_ACQUIRE, "agent");
;             xb_add(&bar[XB_XGEN(b.x)], 1u);
;             asm volatile("s_waitcnt vmcnt(0)" ::: "memory");
.LBB0_763:
	s_or_b64 exec, exec, s[20:21]
	v_mov_b32_e32 v0, 1
	s_waitcnt vmcnt(0)
	global_atomic_add v[162:163], v0, off
	s_waitcnt vmcnt(0)

; DI void xcd_barrier(const XcdBarrier& b) {
;     asm volatile("s_waitcnt vmcnt(0)" ::: "memory");
;     __syncthreads();
;     if (threadIdx.x == 0) {
;         unsigned* bar = b.bar;
;         __builtin_amdgcn_s_waitcnt(0);
;         unsigned nloc = b.st[0], nx = b.st[1];
;         if (nloc == 0u) { xcd_barrier_complete(bar, b.x, nloc, nx); b.st[0] = nloc; b.st[1] = nx; }
.LBB0_921:
	s_waitcnt vmcnt(0)
	v_readlane_b32 s72, v254, 16
	v_readlane_b32 s73, v254, 17
	s_waitcnt vmcnt(0)
	s_barrier
	s_cselect_b32 s98, 1, 0
	v_readfirstlane_b32 s100, v208
	s_lshr_b32 s100, s100, 6
	s_cmp_eq_u32 s100, 1
	s_cbranch_scc0 .Lea_6
	buffer_inv sc1
	s_waitcnt vmcnt(0)
.Lea_6:
	s_cmp_lg_u32 s98, 0
	s_and_saveexec_b64 s[0:1], s[72:73]
	v_readlane_b32 s78, v253, 38
	s_xor_b64 s[8:9], exec, s[0:1]
	v_readlane_b32 s79, v253, 39
	s_cbranch_execz .LBB0_970
	s_add_i32 s0, 0, 0x22000
	v_mov_b32_e32 v0, s0
	s_waitcnt vmcnt(0) expcnt(0) lgkmcnt(0)
	ds_read_b32 v2, v0
	s_add_i32 s0, 0, 0x22004
	v_mov_b32_e32 v0, s0
	ds_read_b32 v0, v0
	s_waitcnt lgkmcnt(1)
	v_cmp_ne_u32_e32 vcc, 0, v2
	s_cbranch_vccnz .LBB0_937
	s_mov_b32 s0, 1
	v_mov_b32_e32 v16, 0
	s_branch .LBB0_925

; DI unsigned xb_ld(unsigned* p)              { return __hip_atomic_load(p, __ATOMIC_RELAXED, __HIP_MEMORY_SCOPE_AGENT); }
; #define XB_SPIN(cond, bar) do { unsigned _sp = 0; while (cond) { __builtin_amdgcn_s_sleep(1); \
;     if ((++_sp & 255u) == 0u) { if (xb_ld(&(bar)[XB_TMO])) break; if (_sp > XB_SPIN_CAP) { atomicAdd(&(bar)[XB_TMO], 1u); break; } } } } while (0)
; DI void xcd_barrier(const XcdBarrier& b) {
;     ...
;             XB_SPIN(xb_ld(&bar[XB_XGEN(b.x)]) == gen, bar);
;             __builtin_amdgcn_fence(__ATOMIC_ACQUIRE, "agent");
;             asm volatile("s_waitcnt vmcnt(0)" ::: "memory");
.LBB0_950:
	s_or_b64 exec, exec, s[20:21]
	s_waitcnt vmcnt(0)
	s_waitcnt vmcnt(0)

; DI void xcd_barrier(const XcdBarrier& b) {
;     ...
;     if (threadIdx.x == 0) {
;         unsigned* bar = b.bar;
;         __builtin_amdgcn_s_waitcnt(0);
;         unsigned nloc = b.st[0], nx = b.st[1];
;         if (nloc == 0u) { xcd_barrier_complete(bar, b.x, nloc, nx); b.st[0] = nloc; b.st[1] = nx; }
.Lea_7:
	s_cmp_lg_u32 s98, 0
	s_and_saveexec_b64 s[14:15], s[72:73]
	s_cbranch_execz .LBB0_1062
	s_add_i32 s0, 0, 0x22000
	v_mov_b32_e32 v0, s0
	s_waitcnt vmcnt(0) expcnt(0) lgkmcnt(0)
	ds_read_b32 v2, v0
	s_add_i32 s0, 0, 0x22004
	v_mov_b32_e32 v0, s0
	ds_read_b32 v0, v0
	s_waitcnt lgkmcnt(1)
	v_cmp_ne_u32_e32 vcc, 0, v2
	s_cbranch_vccnz .LBB0_1030
	s_mov_b32 s0, 1
	v_mov_b32_e32 v16, 0
	s_branch .LBB0_1018

; DI unsigned xb_add(unsigned* p, unsigned v) { return __hip_atomic_fetch_add(p, v, __ATOMIC_RELAXED, __HIP_MEMORY_SCOPE_AGENT); }
; DI void xcd_barrier(const XcdBarrier& b) {
;     ...
;             __builtin_amdgcn_fence(__ATOMIC_ACQUIRE, "agent");
;             xb_add(&bar[XB_XGEN(b.x)], 1u);
;             asm volatile("s_waitcnt vmcnt(0)" ::: "memory");
.LBB0_1061:
	s_or_b64 exec, exec, s[16:17]
	v_mov_b32_e32 v0, 1
	s_waitcnt vmcnt(0)
	global_atomic_add v[162:163], v0, off
	s_waitcnt vmcnt(0)

; DI void xcd_barrier(const XcdBarrier& b) {
;     ...
;     if (threadIdx.x == 0) {
;         unsigned* bar = b.bar;
;         __builtin_amdgcn_s_waitcnt(0);
;         unsigned nloc = b.st[0], nx = b.st[1];
;         if (nloc == 0u) { xcd_barrier_complete(bar, b.x, nloc, nx); b.st[0] = nloc; b.st[1] = nx; }
.Lea_8:
	s_cmp_lg_u32 s98, 0
	s_and_saveexec_b64 s[0:1], s[72:73]
	s_xor_b64 s[8:9], exec, s[0:1]
	s_cbranch_execz .LBB0_1131
	s_add_i32 s0, 0, 0x22000
	v_mov_b32_e32 v0, s0
	s_waitcnt vmcnt(0) expcnt(0) lgkmcnt(0)
	ds_read_b32 v2, v0
	s_add_i32 s0, 0, 0x22004
	v_mov_b32_e32 v0, s0
	ds_read_b32 v0, v0
	s_waitcnt lgkmcnt(1)
	v_cmp_ne_u32_e32 vcc, 0, v2
	s_cbranch_vccnz .LBB0_1098
	s_mov_b32 s0, 1
	v_mov_b32_e32 v16, 0
	s_branch .LBB0_1086

; DI unsigned xb_ld(unsigned* p)              { return __hip_atomic_load(p, __ATOMIC_RELAXED, __HIP_MEMORY_SCOPE_AGENT); }
; #define XB_SPIN(cond, bar) do { unsigned _sp = 0; while (cond) { __builtin_amdgcn_s_sleep(1); \
;     if ((++_sp & 255u) == 0u) { if (xb_ld(&(bar)[XB_TMO])) break; if (_sp > XB_SPIN_CAP) { atomicAdd(&(bar)[XB_TMO], 1u); break; } } } } while (0)
; DI void xcd_barrier(const XcdBarrier& b) {
;     ...
;             XB_SPIN(xb_ld(&bar[XB_XGEN(b.x)]) == gen, bar);
;             __builtin_amdgcn_fence(__ATOMIC_ACQUIRE, "agent");
;             asm volatile("s_waitcnt vmcnt(0)" ::: "memory");
.LBB0_1111:
	s_or_b64 exec, exec, s[4:5]
	s_waitcnt vmcnt(0)
	s_waitcnt vmcnt(0)

; DI unsigned xb_add(unsigned* p, unsigned v) { return __hip_atomic_fetch_add(p, v, __ATOMIC_RELAXED, __HIP_MEMORY_SCOPE_AGENT); }
; DI void xcd_barrier(const XcdBarrier& b) {
;     ...
;             __builtin_amdgcn_fence(__ATOMIC_ACQUIRE, "agent");
;             xb_add(&bar[XB_XGEN(b.x)], 1u);
;             asm volatile("s_waitcnt vmcnt(0)" ::: "memory");
.LBB0_1129:
	s_or_b64 exec, exec, s[4:5]
	v_mov_b32_e32 v0, 1
	s_waitcnt vmcnt(0)
	global_atomic_add v[162:163], v0, off
	s_waitcnt vmcnt(0)
